# attention: unit epilogue staged through LDS with 16-byte stores (was 64 two-byte stores per lane); static s_setprio for waves 4-7 removed
# speedup vs baseline: 1.0093x; 1.0093x over previous
; __device__ __forceinline__ int crow(int r, int hi) { return (r & 3) + 8 * (r >> 2) + 4 * hi; }
; __device__ __forceinline__ void attn_dense_body(const bf16* __restrict__ Qb, const bf16* __restrict__ Kh, const bf16* __restrict__ Vh,
;                                                 bf16* __restrict__ Ob, int seq, char* lds, const int tid, const float mnC) {
;     ...
;   if (hi == 0) li_l[r32] = l_reg; asm volatile("s_waitcnt lgkmcnt(0)" ::: "memory");
;   float rli[16];
; #pragma unroll
;   for (int r = 0; r < 16; ++r) rli[r] = __builtin_amdgcn_rcpf(li_l[crow(r, hi)]);
;   bf16* Ow = Ob + (long)(wid * QBLK) * LDO;
; #pragma unroll
;   for (int r = 0; r < 16; ++r) { const int orow = crow(r, hi);
; #pragma unroll
;     for (int d0 = 0; d0 < 4; ++d0) Ow[(long)orow * LDO + d0 * 32 + r32] = __float2bfloat16(o[d0][r] * rli[r]); }
.LBB0_1036:
	s_or_b64 exec, exec, s[12:13]
	s_waitcnt lgkmcnt(0)
	v_add_u32_e32 v72, v128, v212
	ds_read_b128 v[64:67], v72
	ds_read_b128 v[68:71], v72 offset:32
	ds_read_b128 v[76:79], v72 offset:64
	ds_read_b128 v[80:83], v72 offset:96
	s_add_u32 s2, s2, s6
	s_addc_u32 s3, s3, s7
	s_add_u32 s2, s2, 0xfc00000
	s_addc_u32 s3, s3, 0
	v_lshlrev_b32_e32 v84, 8, v158
	v_lshl_or_b32 v85, v159, 4, v84
	v_lshl_or_b32 v84, v172, 10, v84
	v_lshl_or_b32 v84, v171, 1, v84
	v_lshrrev_b32_e32 v86, 4, v159
	v_add_u32_e32 v86, v86, v158
	v_lshlrev_b32_e32 v86, 11, v86
	v_and_b32_e32 v87, 15, v159
	v_lshl_or_b32 v86, v87, 4, v86
	s_waitcnt lgkmcnt(0)
	v_rcp_f32_e32 v64, v64
	v_rcp_f32_e32 v65, v65
	v_rcp_f32_e32 v66, v66
	v_rcp_f32_e32 v67, v67
	v_rcp_f32_e32 v68, v68
	v_rcp_f32_e32 v69, v69
	v_rcp_f32_e32 v70, v70
	v_rcp_f32_e32 v71, v71
	v_rcp_f32_e32 v76, v76
	v_rcp_f32_e32 v77, v77
	v_rcp_f32_e32 v78, v78
	v_rcp_f32_e32 v79, v79
	v_rcp_f32_e32 v80, v80
	v_rcp_f32_e32 v81, v81
	v_rcp_f32_e32 v82, v82
	v_rcp_f32_e32 v83, v83
	s_nop 0
	v_mul_f32_e32 v88, v0, v64
	v_mul_f32_e32 v89, v1, v65
	v_cvt_pk_bf16_f32 v88, v88, v89
	ds_write_b16 v84, v88 offset:0
	ds_write_b16_d16_hi v84, v88 offset:256
	v_mul_f32_e32 v90, v2, v66
	v_mul_f32_e32 v91, v3, v67
	v_cvt_pk_bf16_f32 v90, v90, v91
	ds_write_b16 v84, v90 offset:512
	ds_write_b16_d16_hi v84, v90 offset:768
	v_mul_f32_e32 v92, v4, v68
	v_mul_f32_e32 v93, v5, v69
	v_cvt_pk_bf16_f32 v92, v92, v93
	ds_write_b16 v84, v92 offset:2048
	ds_write_b16_d16_hi v84, v92 offset:2304
	v_mul_f32_e32 v94, v6, v70
	v_mul_f32_e32 v95, v7, v71
	v_cvt_pk_bf16_f32 v94, v94, v95
	ds_write_b16 v84, v94 offset:2560
	ds_write_b16_d16_hi v84, v94 offset:2816
	v_mul_f32_e32 v88, v8, v76
	v_mul_f32_e32 v89, v9, v77
	v_cvt_pk_bf16_f32 v88, v88, v89
	ds_write_b16 v84, v88 offset:4096
	ds_write_b16_d16_hi v84, v88 offset:4352
	v_mul_f32_e32 v90, v10, v78
	v_mul_f32_e32 v91, v11, v79
	v_cvt_pk_bf16_f32 v90, v90, v91
	ds_write_b16 v84, v90 offset:4608
	ds_write_b16_d16_hi v84, v90 offset:4864
	v_mul_f32_e32 v92, v12, v80
	v_mul_f32_e32 v93, v13, v81
	v_cvt_pk_bf16_f32 v92, v92, v93
	ds_write_b16 v84, v92 offset:6144
	ds_write_b16_d16_hi v84, v92 offset:6400
	v_mul_f32_e32 v94, v14, v82
	v_mul_f32_e32 v95, v15, v83
	v_cvt_pk_bf16_f32 v94, v94, v95
	ds_write_b16 v84, v94 offset:6656
	ds_write_b16_d16_hi v84, v94 offset:6912
	v_mul_f32_e32 v88, v16, v64
	v_mul_f32_e32 v89, v17, v65
	v_cvt_pk_bf16_f32 v88, v88, v89
	ds_write_b16 v84, v88 offset:64
	ds_write_b16_d16_hi v84, v88 offset:320
	v_mul_f32_e32 v90, v18, v66
	v_mul_f32_e32 v91, v19, v67
	v_cvt_pk_bf16_f32 v90, v90, v91
	ds_write_b16 v84, v90 offset:576
	ds_write_b16_d16_hi v84, v90 offset:832
	v_mul_f32_e32 v92, v20, v68
	v_mul_f32_e32 v93, v21, v69
	v_cvt_pk_bf16_f32 v92, v92, v93
	ds_write_b16 v84, v92 offset:2112
	ds_write_b16_d16_hi v84, v92 offset:2368
	v_mul_f32_e32 v94, v22, v70
	v_mul_f32_e32 v95, v23, v71
	v_cvt_pk_bf16_f32 v94, v94, v95
	ds_write_b16 v84, v94 offset:2624
	ds_write_b16_d16_hi v84, v94 offset:2880
	v_mul_f32_e32 v88, v24, v76
	v_mul_f32_e32 v89, v25, v77
	v_cvt_pk_bf16_f32 v88, v88, v89
	ds_write_b16 v84, v88 offset:4160
	ds_write_b16_d16_hi v84, v88 offset:4416
	v_mul_f32_e32 v90, v26, v78
	v_mul_f32_e32 v91, v27, v79
	v_cvt_pk_bf16_f32 v90, v90, v91
	ds_write_b16 v84, v90 offset:4672
	ds_write_b16_d16_hi v84, v90 offset:4928
	v_mul_f32_e32 v92, v28, v80
	v_mul_f32_e32 v93, v29, v81
	v_cvt_pk_bf16_f32 v92, v92, v93
	ds_write_b16 v84, v92 offset:6208
	ds_write_b16_d16_hi v84, v92 offset:6464
	v_mul_f32_e32 v94, v30, v82
	v_mul_f32_e32 v95, v31, v83
	v_cvt_pk_bf16_f32 v94, v94, v95
	ds_write_b16 v84, v94 offset:6720
	ds_write_b16_d16_hi v84, v94 offset:6976
	v_mul_f32_e32 v88, v32, v64
	v_mul_f32_e32 v89, v33, v65
	v_cvt_pk_bf16_f32 v88, v88, v89
	ds_write_b16 v84, v88 offset:128
	ds_write_b16_d16_hi v84, v88 offset:384
	v_mul_f32_e32 v90, v34, v66
	v_mul_f32_e32 v91, v35, v67
	v_cvt_pk_bf16_f32 v90, v90, v91
	ds_write_b16 v84, v90 offset:640
	ds_write_b16_d16_hi v84, v90 offset:896
	v_mul_f32_e32 v92, v36, v68
	v_mul_f32_e32 v93, v37, v69
	v_cvt_pk_bf16_f32 v92, v92, v93
	ds_write_b16 v84, v92 offset:2176
	ds_write_b16_d16_hi v84, v92 offset:2432
	v_mul_f32_e32 v94, v38, v70
	v_mul_f32_e32 v95, v39, v71
	v_cvt_pk_bf16_f32 v94, v94, v95
	ds_write_b16 v84, v94 offset:2688
	ds_write_b16_d16_hi v84, v94 offset:2944
	v_mul_f32_e32 v88, v40, v76
	v_mul_f32_e32 v89, v41, v77
	v_cvt_pk_bf16_f32 v88, v88, v89
	ds_write_b16 v84, v88 offset:4224
	ds_write_b16_d16_hi v84, v88 offset:4480
	v_mul_f32_e32 v90, v42, v78
	v_mul_f32_e32 v91, v43, v79
	v_cvt_pk_bf16_f32 v90, v90, v91
	ds_write_b16 v84, v90 offset:4736
	ds_write_b16_d16_hi v84, v90 offset:4992
	v_mul_f32_e32 v92, v44, v80
	v_mul_f32_e32 v93, v45, v81
	v_cvt_pk_bf16_f32 v92, v92, v93
	ds_write_b16 v84, v92 offset:6272
	ds_write_b16_d16_hi v84, v92 offset:6528
	v_mul_f32_e32 v94, v46, v82
	v_mul_f32_e32 v95, v47, v83
	v_cvt_pk_bf16_f32 v94, v94, v95
	ds_write_b16 v84, v94 offset:6784
	ds_write_b16_d16_hi v84, v94 offset:7040
	v_mul_f32_e32 v88, v48, v64
	v_mul_f32_e32 v89, v49, v65
	v_cvt_pk_bf16_f32 v88, v88, v89
	ds_write_b16 v84, v88 offset:192
	ds_write_b16_d16_hi v84, v88 offset:448
	v_mul_f32_e32 v90, v50, v66
	v_mul_f32_e32 v91, v51, v67
	v_cvt_pk_bf16_f32 v90, v90, v91
	ds_write_b16 v84, v90 offset:704
	ds_write_b16_d16_hi v84, v90 offset:960
	v_mul_f32_e32 v92, v52, v68
	v_mul_f32_e32 v93, v53, v69
	v_cvt_pk_bf16_f32 v92, v92, v93
	ds_write_b16 v84, v92 offset:2240
	ds_write_b16_d16_hi v84, v92 offset:2496
	v_mul_f32_e32 v94, v54, v70
	v_mul_f32_e32 v95, v55, v71
	v_cvt_pk_bf16_f32 v94, v94, v95
	ds_write_b16 v84, v94 offset:2752
	ds_write_b16_d16_hi v84, v94 offset:3008
	v_mul_f32_e32 v88, v56, v76
	v_mul_f32_e32 v89, v57, v77
	v_cvt_pk_bf16_f32 v88, v88, v89
	ds_write_b16 v84, v88 offset:4288
	ds_write_b16_d16_hi v84, v88 offset:4544
	v_mul_f32_e32 v90, v58, v78
	v_mul_f32_e32 v91, v59, v79
	v_cvt_pk_bf16_f32 v90, v90, v91
	ds_write_b16 v84, v90 offset:4800
	ds_write_b16_d16_hi v84, v90 offset:5056
	v_mul_f32_e32 v92, v60, v80
	v_mul_f32_e32 v93, v61, v81
	v_cvt_pk_bf16_f32 v92, v92, v93
	ds_write_b16 v84, v92 offset:6336
	ds_write_b16_d16_hi v84, v92 offset:6592
	v_mul_f32_e32 v94, v62, v82
	v_mul_f32_e32 v95, v63, v83
	v_cvt_pk_bf16_f32 v94, v94, v95
	ds_write_b16 v84, v94 offset:6848
	ds_write_b16_d16_hi v84, v94 offset:7104
	s_waitcnt lgkmcnt(0)
; __device__ __forceinline__ int crow(int r, int hi) { return (r & 3) + 8 * (r >> 2) + 4 * hi; }
; __device__ __forceinline__ int v_st(int k, int c) { const int kk = (k & ~0xC) | ((k & 4) << 1) | ((k & 8) >> 1); return ((kk >> 3) * 4 + (c >> 5)) * 512 + ((kk & 7) * 32 + (c & 31)) * 2; }
; __device__ __forceinline__ int v_rd_base(int lane) { return ((lane & 3) << 3) | (((lane >> 2) & 3) << 6) | (((lane >> 4) & 1) << 5) | (((lane >> 5) & 1) << 8); }
; #define SLOAD0(k0) do { s0_vs0 = ld8(&Vh[(long)((k0) + sr) * LDK + sc]); s0_vs1 = ld8(&Vh[(long)((k0) + 32 + sr) * LDK + sc]); \
;     s0_ks0 = ld8(&Kh[(long)((k0) + sr) * LDK + sc]); s0_ks1 = ld8(&Kh[(long)((k0) + 32 + sr) * LDK + sc]); } while (0)
; __device__ __forceinline__ void attn_dense_body(const bf16* __restrict__ Qb, const bf16* __restrict__ Kh, const bf16* __restrict__ Vh,
;                                                 bf16* __restrict__ Ob, int seq, char* lds, const int tid, const float mnC) {
;   const int wid = tid >> 6, lane = tid & 63, r32 = lane & 31, hi = lane >> 5;
;   bf16* V_lds = (bf16*)lds; bf16* K_lds = (bf16*)(lds + 2 * SHM_V);
;   float* ws = (float*)(lds + 2 * SHM_V + 2 * SHM_K) + wid * 64; float* li_l = ws;
;   float l_reg = 0; f32x16 o[4] = {}; bf16x8 qr[8];
;   const bf16* Qw = Qb + (long)(wid * QBLK + r32) * LDQ + hi * 8;
; #pragma unroll
;   for (int d0 = 0; d0 < 8; ++d0) qr[d0] = ld8(Qw + d0 * 16);
;   const int sr = tid >> 4, sc = (tid & 15) * 8, vst0 = v_st(sr, sc), vst1 = v_st(32 + sr, sc);
;   const int vb0 = (int)(uintptr_t)V_lds + v_rd_base(lane);
;   bf16x8 s0_vs0, s0_vs1, s0_ks0, s0_ks1;
;     ...
;   f32x16 pA0, pA1, pB0, pB1; bf16x8 pa0, pa1, pa2, pa3; const int NT = seq / KVBLK;
;   SLOAD0(0);
;   bf16x8 t1_vs0 = ld8(&Vh[(long)(KVBLK + sr) * LDK + sc]), t1_vs1 = ld8(&Vh[(long)(KVBLK + 32 + sr) * LDK + sc]);
;   bf16x8 t1_ks0 = ld8(&Kh[(long)(KVBLK + sr) * LDK + sc]), t1_ks1 = ld8(&Kh[(long)(KVBLK + 32 + sr) * LDK + sc]);
;   asm volatile("s_waitcnt vmcnt(4)" ::: "memory"); SWRITE0(0); __syncthreads();
;     ...
;   bf16* Ow = Ob + (long)(wid * QBLK) * LDO;
; #pragma unroll
;   for (int r = 0; r < 16; ++r) { const int orow = crow(r, hi);
; #pragma unroll
;     for (int d0 = 0; d0 < 4; ++d0) Ow[(long)orow * LDO + d0 * 32 + r32] = __float2bfloat16(o[d0][r] * rli[r]); }
;   __syncthreads();
	ds_read_b128 v[96:99], v85 offset:0
	ds_read_b128 v[100:103], v85 offset:1024
	ds_read_b128 v[104:107], v85 offset:2048
	ds_read_b128 v[108:111], v85 offset:3072
	ds_read_b128 v[112:115], v85 offset:4096
	ds_read_b128 v[116:119], v85 offset:5120
	ds_read_b128 v[120:123], v85 offset:6144
	ds_read_b128 v[124:127], v85 offset:7168
	s_waitcnt lgkmcnt(7)
	global_store_dwordx4 v86, v[96:99], s[2:3] sc1
	v_add_u32_e32 v87, 0x2000, v86
	s_waitcnt lgkmcnt(6)
	global_store_dwordx4 v87, v[100:103], s[2:3] sc1
	v_add_u32_e32 v95, 0x4000, v86
	s_waitcnt lgkmcnt(5)
	global_store_dwordx4 v95, v[104:107], s[2:3] sc1
	v_add_u32_e32 v87, 0x6000, v86
	s_waitcnt lgkmcnt(4)
	global_store_dwordx4 v87, v[108:111], s[2:3] sc1
	v_add_u32_e32 v95, 0x8000, v86
	s_waitcnt lgkmcnt(3)
	global_store_dwordx4 v95, v[112:115], s[2:3] sc1
	v_add_u32_e32 v87, 0xa000, v86
	s_waitcnt lgkmcnt(2)
	global_store_dwordx4 v87, v[116:119], s[2:3] sc1
	v_add_u32_e32 v95, 0xc000, v86
	s_waitcnt lgkmcnt(1)
	global_store_dwordx4 v95, v[120:123], s[2:3] sc1
	v_add_u32_e32 v87, 0xe000, v86
	s_waitcnt lgkmcnt(0)
	global_store_dwordx4 v87, v[124:127], s[2:3] sc1
	s_add_i32 s8, s8, s5
	s_add_i32 s4, s4, s5
	s_cmpk_gt_i32 s8, 0x1ff
	s_waitcnt vmcnt(63) expcnt(7) lgkmcnt(15)
	s_barrier
	s_cbranch_scc1 .LBB0_1043
.LBB0_1037:
	s_bfe_u32 s12, s8, 0x10002
	s_lshl_b32 s3, s8, 15
	s_lshl_b32 s2, s12, 23
	s_and_b32 s3, s3, 0x7c0000
	s_or_b32 s6, s2, s3
	s_lshl_b32 s2, s8, 8
	s_and_b32 s13, s2, 0x300
	s_ashr_i32 s2, s8, 1
	v_mov_b32_e32 v174, v170
	s_and_b32 s2, s2, 0xffffff80
	s_add_i32 s7, s13, s2
	s_load_dwordx2 s[2:3], s[0:1], 0xb8
	s_ashr_i32 s14, s7, 31
	s_add_u32 s6, s6, s7
	s_addc_u32 s7, 0, s14
	s_lshl_b64 s[6:7], s[6:7], 1
	s_waitcnt lgkmcnt(0)
	s_add_u32 s16, s2, s6
	s_mul_i32 s12, s12, 0x840000
	s_addc_u32 s17, s3, s7
	s_or_b32 s12, s13, s12
	s_add_u32 s14, s2, s12
	s_addc_u32 s15, s3, 0
	s_add_u32 s12, s14, 0xda00000
	v_ashrrev_i32_e32 v16, 4, v174
	v_lshlrev_b32_e32 v26, 3, v174
	s_addc_u32 s13, s15, 0
	v_and_b32_e32 v0, 0x78, v26
	v_ashrrev_i32_e32 v17, 31, v16
	s_add_u32 s14, s14, 0xeb00000
	v_lshlrev_b32_e32 v28, 1, v0
	v_lshlrev_b64 v[32:33], 10, v[16:17]
	s_addc_u32 s15, s15, 0
	v_or_b32_e32 v20, v32, v28
	v_mov_b32_e32 v21, v33
	v_lshl_add_u64 v[0:1], s[14:15], 0, v[20:21]
	global_load_dwordx4 v[0:3], v[0:1], off
	v_add_u32_e32 v18, 32, v16
	v_ashrrev_i32_e32 v19, 31, v18
	v_lshlrev_b64 v[12:13], 10, v[18:19]
	v_or_b32_e32 v12, v12, v28
	v_lshl_add_u64 v[4:5], s[14:15], 0, v[12:13]
	v_lshl_add_u64 v[8:9], s[12:13], 0, v[20:21]
	v_lshl_add_u64 v[12:13], s[12:13], 0, v[12:13]
	global_load_dwordx4 v[4:7], v[4:5], off
	v_ashrrev_i32_e32 v54, 6, v174
	global_load_dwordx4 v[8:11], v[8:9], off
	v_and_b32_e32 v171, 31, v174
	global_load_dwordx4 v[12:15], v[12:13], off
	v_lshlrev_b32_e32 v158, 5, v54
	v_or_b32_e32 v22, v158, v171
	v_ashrrev_i32_e32 v23, 31, v22
	v_bfe_u32 v172, v174, 5, 1
	v_lshlrev_b64 v[22:23], 11, v[22:23]
	v_lshl_add_u64 v[22:23], s[16:17], 0, v[22:23]
	v_lshlrev_b32_e32 v212, 4, v172
	v_lshl_add_u64 v[22:23], v[22:23], 0, v[212:213]
	s_mov_b32 s16, 0xba00000
	v_add_co_u32_e32 v24, vcc, s16, v22
	s_mov_b64 s[16:17], 0xba00000
	s_nop 0
	v_addc_co_u32_e32 v25, vcc, 0, v23, vcc
	global_load_dwordx4 v[124:127], v[24:25], off
	v_lshl_add_u64 v[22:23], v[22:23], 0, s[16:17]
	global_load_dwordx4 v[120:123], v[22:23], off offset:32
	global_load_dwordx4 v[116:119], v[22:23], off offset:64
	global_load_dwordx4 v[112:115], v[22:23], off offset:96
	global_load_dwordx4 v[108:111], v[22:23], off offset:128
	global_load_dwordx4 v[104:107], v[22:23], off offset:160
	global_load_dwordx4 v[100:103], v[22:23], off offset:192
	global_load_dwordx4 v[96:99], v[22:23], off offset:224
	v_and_b32_e32 v17, 0xfffff0, v16
	v_lshlrev_b32_e32 v19, 1, v16
	v_and_b32_e32 v24, 0xfffff0, v18
	v_lshlrev_b32_e32 v25, 1, v18
	v_and_or_b32 v17, v19, 8, v17
	v_and_or_b32 v24, v25, 8, v24
	v_lshrrev_b32_e32 v19, 1, v16
	v_lshrrev_b32_e32 v17, 1, v17
	v_bfe_u32 v22, v26, 5, 2
	v_and_b32_e32 v23, 3, v16
	v_lshrrev_b32_e32 v24, 1, v24
	v_or_b32_e32 v17, v17, v22
	v_and_or_b32 v19, v19, 4, v23
	v_or_b32_e32 v22, v24, v22
	v_lshlrev_b32_e32 v17, 9, v17
	v_lshlrev_b32_e32 v19, 6, v19
	v_and_b32_e32 v23, 48, v28
	v_lshlrev_b32_e32 v22, 9, v22
	s_mov_b64 s[16:17], 0x10000
	v_or3_b32 v17, v17, v19, v23
	v_or3_b32 v19, v22, v19, v23
	v_lshl_add_u64 v[22:23], v[20:21], 0, s[16:17]
	s_mov_b64 s[16:17], 0x18000
	v_lshl_add_u64 v[24:25], s[14:15], 0, v[22:23]
	v_lshl_add_u64 v[20:21], v[20:21], 0, s[16:17]
	v_lshl_add_u64 v[22:23], s[12:13], 0, v[22:23]
	v_add_u32_e32 v175, 0, v17
	v_lshl_add_u64 v[26:27], s[14:15], 0, v[20:21]
	global_load_dwordx4 v[34:37], v[24:25], off
	global_load_dwordx4 v[38:41], v[26:27], off
	v_lshl_add_u64 v[20:21], s[12:13], 0, v[20:21]
	global_load_dwordx4 v[42:45], v[22:23], off
	global_load_dwordx4 v[46:49], v[20:21], off
	s_waitcnt vmcnt(4)
	v_lshlrev_b32_e32 v55, 8, v171
	v_add_u32_e32 v176, 0, v19
	v_or_b32_e32 v50, 32, v212
	v_readfirstlane_b32 s12, v54
	s_cmp_lt_i32 s12, 4
	s_waitcnt vmcnt(15)
	ds_write_b128 v175, v[0:3]
	v_lshlrev_b32_e32 v0, 8, v16
	v_and_b32_e32 v1, 0xf0, v174
	v_bitop3_b32 v0, v28, v0, v1 bitop3:0xde
	v_add_u32_e32 v177, 0, v0
	v_lshlrev_b32_e32 v0, 8, v18
	v_bitop3_b32 v0, v28, v0, v1 bitop3:0xde
	v_add_u32_e32 v178, 0, v0
	v_lshlrev_b32_e32 v0, 4, v174
	v_and_b32_e32 v56, 0xf0, v0
	v_bitop3_b32 v0, v212, v55, v56 bitop3:0xde
	v_add_u32_e32 v179, 0, v0
	s_waitcnt vmcnt(14)
	ds_write_b128 v176, v[4:7]
	s_waitcnt vmcnt(13)
	ds_write_b128 v177, v[8:11] offset:32768
	s_waitcnt vmcnt(12)
	ds_write_b128 v178, v[12:15] offset:32768
	s_waitcnt lgkmcnt(0)
	s_barrier
; #define SWRITE0(b) do { *(bf16x8*)((char*)V_lds + (b) * SHM_V + vst0) = s0_vs0; *(bf16x8*)((char*)V_lds + (b) * SHM_V + vst1) = s0_vs1; const int kc = sc * 2; \
;     *(bf16x8*)((char*)K_lds + (b) * SHM_K + KSWZ(sr, kc)) = s0_ks0; *(bf16x8*)((char*)K_lds + (b) * SHM_K + KSWZ(32 + sr, kc)) = s0_ks1; } while (0)
; #define SWAIT() asm volatile("s_waitcnt vmcnt(0)" ::: "memory")
; __device__ __forceinline__ void qkt(f32x16& p0, f32x16& p1, const bf16* Ks, const bf16x8* qr, int r32, int hi) {
;   p0 = f32x16{}; p1 = f32x16{};
; #pragma unroll
;   for (int d0 = 0; d0 < 8; ++d0) { int cb = (d0 * 16 + hi * 8) * 2;
;     bf16x8 b0 = *reinterpret_cast<const bf16x8*>((const char*)Ks + KSWZ(r32, cb));
;     bf16x8 b1 = *reinterpret_cast<const bf16x8*>((const char*)Ks + KSWZ(32 + r32, cb));
;     p0 = __builtin_amdgcn_mfma_f32_32x32x16_bf16(b0, qr[d0], p0, 0, 0, 0);
;     p1 = __builtin_amdgcn_mfma_f32_32x32x16_bf16(b1, qr[d0], p1, 0, 0, 0); }
; }
; __device__ __forceinline__ void attn_dense_body(const bf16* __restrict__ Qb, const bf16* __restrict__ Kh, const bf16* __restrict__ Vh,
;                                                 bf16* __restrict__ Ob, int seq, char* lds, const int tid, const float mnC) {
;     ...
;   qkt(pA0, pA1, K_lds, qr, r32, hi); partialSM(pA0, pA1, mnC);
;   s0_vs0 = t1_vs0; s0_vs1 = t1_vs1; s0_ks0 = t1_ks0; s0_ks1 = t1_ks1;
;   SWAIT(); SWRITE0(1); __syncthreads();
;   if (__builtin_amdgcn_readfirstlane(wid) >= 4) __builtin_amdgcn_s_setprio(1);
	ds_read_b128 v[0:3], v179 offset:32768
	v_bitop3_b32 v50, v50, v55, v56 bitop3:0xde
	v_add_u32_e32 v182, 0, v50
	ds_read_b128 v[50:53], v182 offset:32768
	s_waitcnt vmcnt(11) lgkmcnt(1)
	v_mfma_f32_32x32x16_bf16 v[16:31], v[0:3], v[124:127], 0
	ds_read_b128 v[0:3], v179 offset:40960
	s_waitcnt vmcnt(10) lgkmcnt(1)
	v_mfma_f32_32x32x16_bf16 v[16:31], v[50:53], v[120:123], v[16:31]
	ds_read_b128 v[50:53], v182 offset:40960
	s_waitcnt lgkmcnt(1)
	v_mfma_f32_32x32x16_bf16 v[0:15], v[0:3], v[124:127], 0
	s_waitcnt lgkmcnt(0)
	v_mfma_f32_32x32x16_bf16 v[0:15], v[50:53], v[120:123], v[0:15]
	v_or_b32_e32 v50, 64, v212
	v_bitop3_b32 v50, v50, v55, v56 bitop3:0xde
	v_add_u32_e32 v183, 0, v50
	ds_read_b128 v[50:53], v183 offset:32768
	s_waitcnt vmcnt(9) lgkmcnt(0)
	v_mfma_f32_32x32x16_bf16 v[16:31], v[50:53], v[116:119], v[16:31]
	ds_read_b128 v[50:53], v183 offset:40960
	s_waitcnt lgkmcnt(0)
	v_mfma_f32_32x32x16_bf16 v[0:15], v[50:53], v[116:119], v[0:15]
	v_or_b32_e32 v50, 0x60, v212
	v_bitop3_b32 v50, v50, v55, v56 bitop3:0xde
	v_add_u32_e32 v184, 0, v50
	ds_read_b128 v[50:53], v184 offset:32768
	s_waitcnt vmcnt(8) lgkmcnt(0)
	v_mfma_f32_32x32x16_bf16 v[16:31], v[50:53], v[112:115], v[16:31]
	ds_read_b128 v[50:53], v184 offset:40960
	s_waitcnt lgkmcnt(0)
	v_mfma_f32_32x32x16_bf16 v[0:15], v[50:53], v[112:115], v[0:15]
	v_or_b32_e32 v50, 0x80, v212
	v_bitop3_b32 v50, v50, v55, v56 bitop3:0xde
	v_add_u32_e32 v185, 0, v50
	ds_read_b128 v[50:53], v185 offset:32768
	s_waitcnt vmcnt(7) lgkmcnt(0)
	v_mfma_f32_32x32x16_bf16 v[16:31], v[50:53], v[108:111], v[16:31]
	ds_read_b128 v[50:53], v185 offset:40960
	s_waitcnt lgkmcnt(0)
	v_mfma_f32_32x32x16_bf16 v[0:15], v[50:53], v[108:111], v[0:15]
	v_or_b32_e32 v50, 0xa0, v212
	v_bitop3_b32 v50, v50, v55, v56 bitop3:0xde
	v_add_u32_e32 v186, 0, v50
	ds_read_b128 v[50:53], v186 offset:32768
	s_waitcnt vmcnt(6) lgkmcnt(0)
	v_mfma_f32_32x32x16_bf16 v[16:31], v[50:53], v[104:107], v[16:31]
	ds_read_b128 v[50:53], v186 offset:40960
	s_waitcnt lgkmcnt(0)
	v_mfma_f32_32x32x16_bf16 v[0:15], v[50:53], v[104:107], v[0:15]
	v_or_b32_e32 v50, 0xc0, v212
	v_bitop3_b32 v50, v50, v55, v56 bitop3:0xde
	v_add_u32_e32 v180, 0, v50
	ds_read_b128 v[50:53], v180 offset:32768
	s_waitcnt vmcnt(5) lgkmcnt(0)
	v_mfma_f32_32x32x16_bf16 v[16:31], v[50:53], v[100:103], v[16:31]
	ds_read_b128 v[50:53], v180 offset:40960
	s_waitcnt lgkmcnt(0)
	v_mfma_f32_32x32x16_bf16 v[0:15], v[50:53], v[100:103], v[0:15]
	v_or_b32_e32 v50, 0xe0, v212
	v_bitop3_b32 v50, v50, v55, v56 bitop3:0xde
	v_add_u32_e32 v181, 0, v50
	ds_read_b128 v[50:53], v181 offset:32768
	s_waitcnt vmcnt(4) lgkmcnt(0)
	v_mfma_f32_32x32x16_bf16 v[16:31], v[50:53], v[96:99], v[16:31]
	ds_read_b128 v[50:53], v181 offset:40960
	s_waitcnt vmcnt(0)
	s_waitcnt vmcnt(3)
	ds_write_b128 v175, v[34:37] offset:16384
	s_waitcnt vmcnt(2)
	ds_write_b128 v176, v[38:41] offset:16384
	s_waitcnt vmcnt(1)
	ds_write_b128 v177, v[42:45] offset:49152
	s_waitcnt vmcnt(0)
	ds_write_b128 v178, v[46:49] offset:49152
	s_waitcnt lgkmcnt(0)
	s_barrier
	v_mfma_f32_32x32x16_bf16 v[0:15], v[50:53], v[96:99], v[0:15]
	s_cbranch_scc1 .LBB0_1039
	s_setprio 0
